# decay weights applied when staging v into LDS (fwd/bwd scaled images), MFMA loop is tr-reads+MFMA only; plus write-through ACT stores
# speedup vs baseline: 1.0145x; 1.0041x over previous
.LBB0_959:
	s_cmpk_eq_i32 s52, 0x180
	s_mov_b64 s[12:13], -1
	s_barrier
	ds_write_b128 v238, v[104:107]
	ds_write_b128 v239, v[108:111]
	ds_write_b128 v240, v[112:115]
	ds_write_b128 v241, v[116:119]
	ds_write_b128 v242, v[120:123]
	ds_write_b128 v243, v[124:127]
	ds_write_b128 v244, v[128:131]
	ds_write_b128 v245, v[132:135]
	v_lshrrev_b32_e32 v0, 3, v230
	v_add_u32_e32 v1, s52, v0
	v_add_u32_e32 v2, 64, v1
	v_sub_u32_e32 v3, 0x1ff, v1
	v_sub_u32_e32 v4, 0x1ff, v2
	v_cvt_f32_u32_e32 v1, v1
	v_cvt_f32_u32_e32 v2, v2
	v_cvt_f32_u32_e32 v3, v3
	v_cvt_f32_u32_e32 v4, v4
	v_mul_f32_e32 v1, v254, v1
	v_mul_f32_e32 v2, v254, v2
	v_mul_f32_e32 v3, v253, v3
	v_mul_f32_e32 v4, v253, v4
	v_exp_f32_e32 v1, v1
	v_exp_f32_e32 v2, v2
	v_exp_f32_e32 v3, v3
	v_exp_f32_e32 v4, v4
	v_lshlrev_b32_e32 v8, 16, v136
	v_and_b32_e32 v9, 0xffff0000, v136
	v_lshlrev_b32_e32 v10, 16, v137
	v_and_b32_e32 v11, 0xffff0000, v137
	v_lshlrev_b32_e32 v12, 16, v138
	v_and_b32_e32 v13, 0xffff0000, v138
	v_lshlrev_b32_e32 v14, 16, v139
	v_and_b32_e32 v15, 0xffff0000, v139
	v_mul_f32_e32 v5, v3, v8
	v_mul_f32_e32 v6, v3, v9
	v_cvt_pk_bf16_f32 v24, v5, v6
	v_mul_f32_e32 v5, v3, v10
	v_mul_f32_e32 v6, v3, v11
	v_cvt_pk_bf16_f32 v25, v5, v6
	v_mul_f32_e32 v5, v3, v12
	v_mul_f32_e32 v6, v3, v13
	v_cvt_pk_bf16_f32 v26, v5, v6
	v_mul_f32_e32 v5, v3, v14
	v_mul_f32_e32 v6, v3, v15
	v_cvt_pk_bf16_f32 v27, v5, v6
	ds_write_b128 v246, v[24:27]
	v_mul_f32_e32 v5, v1, v8
	v_mul_f32_e32 v6, v1, v9
	v_cvt_pk_bf16_f32 v28, v5, v6
	v_mul_f32_e32 v5, v1, v10
	v_mul_f32_e32 v6, v1, v11
	v_cvt_pk_bf16_f32 v29, v5, v6
	v_mul_f32_e32 v5, v1, v12
	v_mul_f32_e32 v6, v1, v13
	v_cvt_pk_bf16_f32 v30, v5, v6
	v_mul_f32_e32 v5, v1, v14
	v_mul_f32_e32 v6, v1, v15
	v_cvt_pk_bf16_f32 v31, v5, v6
	ds_write_b128 v246, v[28:31] offset:20480
	v_lshlrev_b32_e32 v16, 16, v140
	v_and_b32_e32 v17, 0xffff0000, v140
	v_lshlrev_b32_e32 v18, 16, v141
	v_and_b32_e32 v19, 0xffff0000, v141
	v_lshlrev_b32_e32 v20, 16, v142
	v_and_b32_e32 v21, 0xffff0000, v142
	v_lshlrev_b32_e32 v22, 16, v143
	v_and_b32_e32 v23, 0xffff0000, v143
	v_mul_f32_e32 v5, v4, v16
	v_mul_f32_e32 v6, v4, v17
	v_cvt_pk_bf16_f32 v32, v5, v6
	v_mul_f32_e32 v5, v4, v18
	v_mul_f32_e32 v6, v4, v19
	v_cvt_pk_bf16_f32 v33, v5, v6
	v_mul_f32_e32 v5, v4, v20
	v_mul_f32_e32 v6, v4, v21
	v_cvt_pk_bf16_f32 v34, v5, v6
	v_mul_f32_e32 v5, v4, v22
	v_mul_f32_e32 v6, v4, v23
	v_cvt_pk_bf16_f32 v35, v5, v6
	ds_write_b128 v247, v[32:35]
	v_mul_f32_e32 v5, v2, v16
	v_mul_f32_e32 v6, v2, v17
	v_cvt_pk_bf16_f32 v36, v5, v6
	v_mul_f32_e32 v5, v2, v18
	v_mul_f32_e32 v6, v2, v19
	v_cvt_pk_bf16_f32 v37, v5, v6
	v_mul_f32_e32 v5, v2, v20
	v_mul_f32_e32 v6, v2, v21
	v_cvt_pk_bf16_f32 v38, v5, v6
	v_mul_f32_e32 v5, v2, v22
	v_mul_f32_e32 v6, v2, v23
	v_cvt_pk_bf16_f32 v39, v5, v6
	ds_write_b128 v247, v[36:39] offset:20480
	s_waitcnt lgkmcnt(0)
	s_barrier
	s_cbranch_scc1 .LBB0_961
	v_lshl_add_u64 v[0:1], v[228:229], 0, s[0:1]
	v_lshl_add_u64 v[4:5], v[226:227], 0, s[0:1]
	v_lshl_add_u64 v[8:9], v[224:225], 0, s[0:1]
	v_lshl_add_u64 v[12:13], v[222:223], 0, s[0:1]
	v_lshl_add_u64 v[16:17], v[220:221], 0, s[0:1]
	v_lshl_add_u64 v[20:21], v[218:219], 0, s[0:1]
	v_lshl_add_u64 v[24:25], v[216:217], 0, s[0:1]
	v_lshl_add_u64 v[28:29], v[214:215], 0, s[0:1]
	v_lshl_add_u64 v[32:33], v[212:213], 0, s[0:1]
	v_lshl_add_u64 v[36:37], v[210:211], 0, s[0:1]
	global_load_dwordx4 v[0:3], v[0:1], off
	s_mov_b64 s[12:13], 0
	global_load_dwordx4 v[4:7], v[4:5], off
	s_nop 0
	global_load_dwordx4 v[8:11], v[8:9], off
	s_nop 0
	global_load_dwordx4 v[12:15], v[12:13], off
	s_nop 0
	global_load_dwordx4 v[16:19], v[16:17], off
	s_nop 0
	global_load_dwordx4 v[20:23], v[20:21], off
	s_nop 0
	global_load_dwordx4 v[24:27], v[24:25], off
	s_nop 0
	global_load_dwordx4 v[28:31], v[28:29], off
	s_nop 0
	global_load_dwordx4 v[32:35], v[32:33], off
	s_nop 0
	global_load_dwordx4 v[36:39], v[36:37], off

.LBB0_965:
	v_add_u32_e32 v236, v234, v232
	s_addk_i32 s52, 0x80
	ds_read_b64_tr_b16 v[104:105], v248
	ds_read_b64_tr_b16 v[106:107], v248 offset:2560
	ds_read_b64_tr_b16 v[108:109], v248 offset:20480
	ds_read_b64_tr_b16 v[110:111], v248 offset:23040
	ds_read_b64_tr_b16 v[120:121], v236
	ds_read_b64_tr_b16 v[122:123], v236 offset:8704
	ds_read_b64_tr_b16 v[124:125], v236 offset:32
	ds_read_b64_tr_b16 v[126:127], v236 offset:8736
	ds_read_b64_tr_b16 v[128:129], v236 offset:64
	ds_read_b64_tr_b16 v[130:131], v236 offset:8768
	ds_read_b64_tr_b16 v[132:133], v236 offset:96
	ds_read_b64_tr_b16 v[134:135], v236 offset:8800
	s_waitcnt lgkmcnt(6)
	v_mfma_f32_16x16x32_bf16 v[100:103], v[120:123], v[104:107], v[100:103]
	v_mfma_f32_16x16x32_bf16 v[68:71], v[120:123], v[108:111], v[68:71]
	ds_read_b64_tr_b16 v[136:137], v236 offset:128
	ds_read_b64_tr_b16 v[138:139], v236 offset:8832
	v_lshl_add_u64 v[210:211], v[210:211], 0, s[6:7]
	s_waitcnt lgkmcnt(6)
	v_mfma_f32_16x16x32_bf16 v[96:99], v[124:127], v[104:107], v[96:99]
	v_mfma_f32_16x16x32_bf16 v[64:67], v[124:127], v[108:111], v[64:67]
	ds_read_b64_tr_b16 v[120:121], v236 offset:160
	ds_read_b64_tr_b16 v[122:123], v236 offset:8864
	s_waitcnt lgkmcnt(6)
	v_mfma_f32_16x16x32_bf16 v[88:91], v[128:131], v[104:107], v[88:91]
	v_mfma_f32_16x16x32_bf16 v[56:59], v[128:131], v[108:111], v[56:59]
	ds_read_b64_tr_b16 v[124:125], v236 offset:192
	ds_read_b64_tr_b16 v[126:127], v236 offset:8896
	s_waitcnt lgkmcnt(6)
	v_mfma_f32_16x16x32_bf16 v[80:83], v[132:135], v[104:107], v[80:83]
	v_mfma_f32_16x16x32_bf16 v[52:55], v[132:135], v[108:111], v[52:55]
	ds_read_b64_tr_b16 v[128:129], v236 offset:224
	ds_read_b64_tr_b16 v[130:131], v236 offset:8928
	ds_read_b64_tr_b16 v[112:113], v248 offset:5120
	ds_read_b64_tr_b16 v[114:115], v248 offset:7680
	ds_read_b64_tr_b16 v[116:117], v248 offset:25600
	ds_read_b64_tr_b16 v[118:119], v248 offset:28160
	v_lshl_add_u64 v[212:213], v[212:213], 0, s[6:7]
	s_waitcnt lgkmcnt(10)
	v_mfma_f32_16x16x32_bf16 v[92:95], v[136:139], v[104:107], v[92:95]
	v_mfma_f32_16x16x32_bf16 v[60:63], v[136:139], v[108:111], v[60:63]
	ds_read_b64_tr_b16 v[132:133], v249
	ds_read_b64_tr_b16 v[134:135], v249 offset:8704
	s_waitcnt lgkmcnt(10)
	v_mfma_f32_16x16x32_bf16 v[84:87], v[120:123], v[104:107], v[84:87]
	v_mfma_f32_16x16x32_bf16 v[48:51], v[120:123], v[108:111], v[48:51]
	ds_read_b64_tr_b16 v[136:137], v249 offset:32
	ds_read_b64_tr_b16 v[138:139], v249 offset:8736
	s_waitcnt lgkmcnt(10)
	v_mfma_f32_16x16x32_bf16 v[76:79], v[124:127], v[104:107], v[76:79]
	v_mfma_f32_16x16x32_bf16 v[44:47], v[124:127], v[108:111], v[44:47]
	ds_read_b64_tr_b16 v[120:121], v249 offset:64
	ds_read_b64_tr_b16 v[122:123], v249 offset:8768
	v_lshl_add_u64 v[214:215], v[214:215], 0, s[6:7]
	s_waitcnt lgkmcnt(10)
	v_mfma_f32_16x16x32_bf16 v[72:75], v[128:131], v[104:107], v[72:75]
	v_mfma_f32_16x16x32_bf16 v[40:43], v[128:131], v[108:111], v[40:43]
	ds_read_b64_tr_b16 v[124:125], v249 offset:96
	ds_read_b64_tr_b16 v[126:127], v249 offset:8800
	s_waitcnt lgkmcnt(6)
	v_mfma_f32_16x16x32_bf16 v[100:103], v[132:135], v[112:115], v[100:103]
	v_mfma_f32_16x16x32_bf16 v[68:71], v[132:135], v[116:119], v[68:71]
	ds_read_b64_tr_b16 v[128:129], v249 offset:128
	ds_read_b64_tr_b16 v[130:131], v249 offset:8832
	s_waitcnt lgkmcnt(6)
	v_mfma_f32_16x16x32_bf16 v[96:99], v[136:139], v[112:115], v[96:99]
	v_mfma_f32_16x16x32_bf16 v[64:67], v[136:139], v[116:119], v[64:67]
	ds_read_b64_tr_b16 v[132:133], v249 offset:160
	ds_read_b64_tr_b16 v[134:135], v249 offset:8864
	v_lshl_add_u64 v[216:217], v[216:217], 0, s[6:7]
	s_waitcnt lgkmcnt(6)
	v_mfma_f32_16x16x32_bf16 v[88:91], v[120:123], v[112:115], v[88:91]
	v_mfma_f32_16x16x32_bf16 v[56:59], v[120:123], v[116:119], v[56:59]
	ds_read_b64_tr_b16 v[136:137], v249 offset:192
	ds_read_b64_tr_b16 v[138:139], v249 offset:8896
	s_waitcnt lgkmcnt(6)
	v_mfma_f32_16x16x32_bf16 v[80:83], v[124:127], v[112:115], v[80:83]
	v_mfma_f32_16x16x32_bf16 v[52:55], v[124:127], v[116:119], v[52:55]
	ds_read_b64_tr_b16 v[120:121], v249 offset:224
	ds_read_b64_tr_b16 v[122:123], v249 offset:8928
	ds_read_b64_tr_b16 v[104:105], v248 offset:10240
	ds_read_b64_tr_b16 v[106:107], v248 offset:12800
	ds_read_b64_tr_b16 v[108:109], v248 offset:30720
	ds_read_b64_tr_b16 v[110:111], v248 offset:33280
	s_waitcnt lgkmcnt(10)
	v_mfma_f32_16x16x32_bf16 v[92:95], v[128:131], v[112:115], v[92:95]
	v_mfma_f32_16x16x32_bf16 v[60:63], v[128:131], v[116:119], v[60:63]
	ds_read_b64_tr_b16 v[124:125], v250
	ds_read_b64_tr_b16 v[126:127], v250 offset:8704
	v_lshl_add_u64 v[218:219], v[218:219], 0, s[6:7]
	s_waitcnt lgkmcnt(10)
	v_mfma_f32_16x16x32_bf16 v[84:87], v[132:135], v[112:115], v[84:87]
	v_mfma_f32_16x16x32_bf16 v[48:51], v[132:135], v[116:119], v[48:51]
	ds_read_b64_tr_b16 v[128:129], v250 offset:32
	ds_read_b64_tr_b16 v[130:131], v250 offset:8736
	s_waitcnt lgkmcnt(10)
	v_mfma_f32_16x16x32_bf16 v[76:79], v[136:139], v[112:115], v[76:79]
	v_mfma_f32_16x16x32_bf16 v[44:47], v[136:139], v[116:119], v[44:47]
	ds_read_b64_tr_b16 v[132:133], v250 offset:64
	ds_read_b64_tr_b16 v[134:135], v250 offset:8768
	s_waitcnt lgkmcnt(10)
	v_mfma_f32_16x16x32_bf16 v[72:75], v[120:123], v[112:115], v[72:75]
	v_mfma_f32_16x16x32_bf16 v[40:43], v[120:123], v[116:119], v[40:43]
	ds_read_b64_tr_b16 v[136:137], v250 offset:96
	ds_read_b64_tr_b16 v[138:139], v250 offset:8800
	v_lshl_add_u64 v[220:221], v[220:221], 0, s[6:7]
	s_waitcnt lgkmcnt(6)
	v_mfma_f32_16x16x32_bf16 v[100:103], v[124:127], v[104:107], v[100:103]
	v_mfma_f32_16x16x32_bf16 v[68:71], v[124:127], v[108:111], v[68:71]
	ds_read_b64_tr_b16 v[120:121], v250 offset:128
	ds_read_b64_tr_b16 v[122:123], v250 offset:8832
	s_waitcnt lgkmcnt(6)
	v_mfma_f32_16x16x32_bf16 v[96:99], v[128:131], v[104:107], v[96:99]
	v_mfma_f32_16x16x32_bf16 v[64:67], v[128:131], v[108:111], v[64:67]
	ds_read_b64_tr_b16 v[124:125], v250 offset:160
	ds_read_b64_tr_b16 v[126:127], v250 offset:8864
	s_waitcnt lgkmcnt(6)
	v_mfma_f32_16x16x32_bf16 v[88:91], v[132:135], v[104:107], v[88:91]
	v_mfma_f32_16x16x32_bf16 v[56:59], v[132:135], v[108:111], v[56:59]
	ds_read_b64_tr_b16 v[128:129], v250 offset:192
	ds_read_b64_tr_b16 v[130:131], v250 offset:8896
	v_lshl_add_u64 v[222:223], v[222:223], 0, s[6:7]
	s_waitcnt lgkmcnt(6)
	v_mfma_f32_16x16x32_bf16 v[80:83], v[136:139], v[104:107], v[80:83]
	v_mfma_f32_16x16x32_bf16 v[52:55], v[136:139], v[108:111], v[52:55]
	ds_read_b64_tr_b16 v[132:133], v250 offset:224
	ds_read_b64_tr_b16 v[134:135], v250 offset:8928
	ds_read_b64_tr_b16 v[112:113], v248 offset:15360
	ds_read_b64_tr_b16 v[114:115], v248 offset:17920
	ds_read_b64_tr_b16 v[116:117], v248 offset:35840
	ds_read_b64_tr_b16 v[118:119], v248 offset:38400
	s_waitcnt lgkmcnt(10)
	v_mfma_f32_16x16x32_bf16 v[92:95], v[120:123], v[104:107], v[92:95]
	v_mfma_f32_16x16x32_bf16 v[60:63], v[120:123], v[108:111], v[60:63]
	ds_read_b64_tr_b16 v[136:137], v251
	ds_read_b64_tr_b16 v[138:139], v251 offset:8704
	s_waitcnt lgkmcnt(10)
	v_mfma_f32_16x16x32_bf16 v[84:87], v[124:127], v[104:107], v[84:87]
	v_mfma_f32_16x16x32_bf16 v[48:51], v[124:127], v[108:111], v[48:51]
	ds_read_b64_tr_b16 v[120:121], v251 offset:32
	ds_read_b64_tr_b16 v[122:123], v251 offset:8736
	v_lshl_add_u64 v[224:225], v[224:225], 0, s[6:7]
	s_waitcnt lgkmcnt(10)
	v_mfma_f32_16x16x32_bf16 v[76:79], v[128:131], v[104:107], v[76:79]
	v_mfma_f32_16x16x32_bf16 v[44:47], v[128:131], v[108:111], v[44:47]
	ds_read_b64_tr_b16 v[124:125], v251 offset:64
	ds_read_b64_tr_b16 v[126:127], v251 offset:8768
	s_waitcnt lgkmcnt(10)
	v_mfma_f32_16x16x32_bf16 v[72:75], v[132:135], v[104:107], v[72:75]
	v_mfma_f32_16x16x32_bf16 v[40:43], v[132:135], v[108:111], v[40:43]
	ds_read_b64_tr_b16 v[128:129], v251 offset:96
	ds_read_b64_tr_b16 v[130:131], v251 offset:8800
	s_waitcnt lgkmcnt(6)
	v_mfma_f32_16x16x32_bf16 v[100:103], v[136:139], v[112:115], v[100:103]
	v_mfma_f32_16x16x32_bf16 v[68:71], v[136:139], v[116:119], v[68:71]
	ds_read_b64_tr_b16 v[132:133], v251 offset:128
	ds_read_b64_tr_b16 v[134:135], v251 offset:8832
	v_lshl_add_u64 v[226:227], v[226:227], 0, s[6:7]
	s_waitcnt lgkmcnt(6)
	v_mfma_f32_16x16x32_bf16 v[96:99], v[120:123], v[112:115], v[96:99]
	v_mfma_f32_16x16x32_bf16 v[64:67], v[120:123], v[116:119], v[64:67]
	ds_read_b64_tr_b16 v[136:137], v251 offset:160
	ds_read_b64_tr_b16 v[138:139], v251 offset:8864
	s_waitcnt lgkmcnt(6)
	v_mfma_f32_16x16x32_bf16 v[88:91], v[124:127], v[112:115], v[88:91]
	v_mfma_f32_16x16x32_bf16 v[56:59], v[124:127], v[116:119], v[56:59]
	ds_read_b64_tr_b16 v[120:121], v251 offset:192
	ds_read_b64_tr_b16 v[122:123], v251 offset:8896
	s_waitcnt lgkmcnt(6)
	v_mfma_f32_16x16x32_bf16 v[80:83], v[128:131], v[112:115], v[80:83]
	v_mfma_f32_16x16x32_bf16 v[52:55], v[128:131], v[116:119], v[52:55]
	ds_read_b64_tr_b16 v[124:125], v251 offset:224
	ds_read_b64_tr_b16 v[126:127], v251 offset:8928
	v_lshl_add_u64 v[228:229], v[228:229], 0, s[6:7]
	s_waitcnt lgkmcnt(6)
	v_mfma_f32_16x16x32_bf16 v[92:95], v[132:135], v[112:115], v[92:95]
	v_mfma_f32_16x16x32_bf16 v[60:63], v[132:135], v[116:119], v[60:63]
	s_waitcnt lgkmcnt(4)
	v_mfma_f32_16x16x32_bf16 v[84:87], v[136:139], v[112:115], v[84:87]
	v_mfma_f32_16x16x32_bf16 v[48:51], v[136:139], v[116:119], v[48:51]
	s_waitcnt lgkmcnt(2)
	v_mfma_f32_16x16x32_bf16 v[76:79], v[120:123], v[112:115], v[76:79]
	v_mfma_f32_16x16x32_bf16 v[44:47], v[120:123], v[116:119], v[44:47]
	s_waitcnt lgkmcnt(0)
	v_mfma_f32_16x16x32_bf16 v[72:75], v[124:127], v[112:115], v[72:75]
	v_mfma_f32_16x16x32_bf16 v[40:43], v[124:127], v[116:119], v[40:43]
	s_cmpk_eq_i32 s52, 0x200
	s_cbranch_scc1 .LBB0_957
	s_waitcnt vmcnt(2)
	v_mov_b64_e32 v[134:135], v[30:31]
	v_mov_b64_e32 v[130:131], v[26:27]
	v_mov_b64_e32 v[126:127], v[22:23]
	v_mov_b64_e32 v[122:123], v[18:19]
	v_mov_b64_e32 v[118:119], v[14:15]
	v_mov_b64_e32 v[114:115], v[10:11]
	v_mov_b64_e32 v[110:111], v[6:7]
	v_mov_b64_e32 v[106:107], v[2:3]
	s_waitcnt vmcnt(0)
	v_mov_b64_e32 v[142:143], v[38:39]
	v_mov_b64_e32 v[138:139], v[34:35]
	v_mov_b64_e32 v[132:133], v[28:29]
	v_mov_b64_e32 v[128:129], v[24:25]
	v_mov_b64_e32 v[124:125], v[20:21]
	v_mov_b64_e32 v[120:121], v[16:17]
	v_mov_b64_e32 v[116:117], v[12:13]
	v_mov_b64_e32 v[112:113], v[8:9]
	v_mov_b64_e32 v[108:109], v[4:5]
	v_mov_b64_e32 v[104:105], v[0:1]
	v_mov_b64_e32 v[140:141], v[36:37]
	v_mov_b64_e32 v[136:137], v[32:33]
	s_branch .LBB0_959
